# MLA item order: the 32 workgroups of an XCD take the 32 query-tile pairs of ONE (batch, head) per round (K/V stream shared through that XCD's L2) instead of 8 heads x 4 pairs
# baseline (speedup 1.0000x reference)
; template <bool MLA> __device__ __forceinline__ void attn_unit(const AttnP& P, int b, int hh, int qb, LAS char* lds) {
;     ...
;     const int qlo = q0 + wid * 32, qm = qlo + r32 - 4 * hi;
;     bf16x8 qr[NQF];
;     const size_t qrow = rowbase + qlo + r32;
;     if constexpr (MLA) {
; #pragma unroll
;         for (int d0 = 0; d0 < 8; ++d0) qr[d0] = *(const bf16x8*)(P.QN + qrow * 2048 + hh * 128 + d0 * 16 + hi * 8);
; #pragma unroll
;         for (int d0 = 0; d0 < 4; ++d0) qr[8 + d0] = *(const bf16x8*)(P.QR + qrow * 1024 + hh * 64 + d0 * 16 + hi * 8);
;     } else {
; #pragma unroll
;         for (int d0 = 0; d0 < 4; ++d0) qr[d0] = *(const bf16x8*)(P.QS + qrow * 2048 + hh * 64 + d0 * 16 + hi * 8);
;         if (tid < 128) bias_l[tid] = P.rel[(int)T5B[tid] * 32 + hh] * (1.0f / SCALE);
;     }
;     bf16x8 sk0, sv0;
;     const int sr8 = tid >> 3, ch8 = tid & 7;
;     const bf16_t* Kg; const bf16_t* Vg; const bf16_t* Rg = nullptr;
;     unsigned okA = 0, okB = 0, orp = 0, ovA = 0, ovB = 0;
;     if constexpr (MLA) {
;         Kg = P.KN + rowbase * 2048 + hh * 128; Vg = P.V + rowbase * 2048 + hh * 128; Rg = P.KR + rowbase * 64;
;         { const int rA = 4 * wid + (lane >> 4), rB = rA + 32, cp = lane & 15; okA = (unsigned)(rA * 2048 + ((cp ^ (rA & 7)) << 3)); okB = (unsigned)(rB * 2048 + ((cp ^ (rB & 7)) << 3)); }
;         { const int rr = 8 * wid + (lane >> 3), cp = lane & 7; orp = (unsigned)(rr * 64 + ((cp ^ (rr & 7)) << 3)); }
;         { const int stA = 2 * wid + (lane >> 5), stB = stA + 16; const int kl = (lane & 31) >> 2, c8 = 8 * (lane & 3);
;           const int kkA = (stA >> 2) * 8 + kl, kkB = (stB >> 2) * 8 + kl;
;           const int kA = (kkA & ~0xC) | ((kkA & 4) << 1) | ((kkA & 8) >> 1), kB = (kkB & ~0xC) | ((kkB & 4) << 1) | ((kkB & 8) >> 1);
;           ovA = (unsigned)(kA * 2048 + 32 * (stA & 3) + c8); ovB = (unsigned)(kB * 2048 + 32 * (stB & 3) + c8); }
;     } else { Kg = P.KS + (rowbase + sr8) * 256 + (hh >> 3) * 64 + ch8 * 8; Vg = P.VS + (rowbase + sr8) * 256 + (hh >> 3) * 64 + ch8 * 8; }
;     const int kws = KSWZ64(sr8, ch8), vst0 = v_st<NCB>(sr8, ch8 * 8);
;     ...
;     float m_reg = MLA ? 0.f : P.sinks[hh] * (1.0f / SCALE), l_reg = MLA ? 0.f : 1.f;
;     f32x16 o[NCB];
; #pragma unroll
;     for (int d = 0; d < NCB; ++d) o[d] = f32x16{};
;     const int vb0 = (int)(uintptr_t)V_lds + v_rd_base(lane);
.Lm16_unit:
	s_bfe_u32 s33, s28, 0x50003
	s_cmp_eq_u32 s29, 0
	s_cbranch_scc0 .Lm16_qb_ok
	s_sub_u32 s33, 63, s33
.Lm16_qb_ok:
	s_and_b32 s36, s28, 7
	s_lshr_b32 s37, s28, 8
	s_lshl_b32 s37, s37, 3
	s_or_b32 s36, s36, s37
	s_and_b32 s63, s36, 15
	s_lshr_b32 s64, s36, 4
	s_lshl_b32 s40, s33, 2
	s_add_u32 s40, s40, 4
	s_lshl_b32 s43, s33, 8
	s_lshl_b32 s36, s4, 5
	s_add_u32 s43, s43, s36
	s_lshl_b32 s36, s64, 14
	s_add_u32 s36, s36, s43
	s_lshl_b32 s37, s36, 12
	s_lshl_b32 s59, s63, 8
	s_add_u32 s37, s37, s59
	s_add_u32 s66, s6, s37
	s_addc_u32 s67, s7, 0
	s_lshl_b32 s37, s36, 11
	s_lshl_b32 s59, s63, 7
	s_add_u32 s37, s37, s59
	s_add_u32 s68, s8, s37
	s_addc_u32 s69, s9, 0
	s_lshl_b32 s37, s64, 26
	s_lshl_b32 s59, s63, 8
	s_add_u32 s37, s37, s59
	s_add_u32 s46, s12, s37
	s_addc_u32 s47, s13, 0
	s_add_u32 s48, s16, s37
	s_addc_u32 s49, s17, 0
	s_lshl_b32 s37, s64, 21
	s_add_u32 s50, s14, s37
	s_addc_u32 s51, s15, 0
	global_load_dwordx4 v[66:69], v237, s[66:67] offset:0
	global_load_dwordx4 v[70:73], v237, s[66:67] offset:64
	global_load_dwordx4 v[74:77], v237, s[66:67] offset:128
	global_load_dwordx4 v[78:81], v237, s[66:67] offset:192
	global_load_dwordx4 v[82:85], v239, s[68:69] offset:0
	global_load_dwordx4 v[86:89], v239, s[68:69] offset:64
	global_load_dwordx4 v[90:93], v238, s[66:67] offset:0
	global_load_dwordx4 v[94:97], v238, s[66:67] offset:64
	global_load_dwordx4 v[98:101], v238, s[66:67] offset:128
	global_load_dwordx4 v[102:105], v238, s[66:67] offset:192
	global_load_dwordx4 v[106:109], v240, s[68:69] offset:0
	global_load_dwordx4 v[110:113], v240, s[68:69] offset:64
	s_mov_b32 s70, 0x8000
	s_mov_b32 s71, 0
	s_add_i32 s36, s5, s70
	s_mov_b32 m0, s36
	s_nop 0
	global_load_lds_dwordx4 v232, s[46:47]
	s_add_i32 m0, s36, 0x2000
	s_nop 0
	global_load_lds_dwordx4 v233, s[46:47]
	s_add_i32 m0, s36, 0x4000
	s_nop 0
	global_load_lds_dwordx4 v234, s[50:51]
	s_add_i32 s36, s5, s71
	s_mov_b32 m0, s36
	s_nop 0
	global_load_lds_dwordx4 v235, s[48:49]
	s_add_i32 m0, s36, 0x2000
	s_nop 0
	global_load_lds_dwordx4 v236, s[48:49]
	s_add_u32 s46, s46, 0x40000
	s_addc_u32 s47, s47, 0
	s_add_u32 s48, s48, 0x40000
	s_addc_u32 s49, s49, 0
	s_add_u32 s50, s50, 0x2000
	s_addc_u32 s51, s51, 0
	v_mov_b32_e32 v2, 0
	v_mov_b32_e32 v3, 0
	v_mov_b32_e32 v4, 0
	v_mov_b32_e32 v5, 0
	v_mov_b32_e32 v6, 0
	v_mov_b32_e32 v7, 0
	v_mov_b32_e32 v8, 0
	v_mov_b32_e32 v9, 0
	v_mov_b32_e32 v10, 0
	v_mov_b32_e32 v11, 0
	v_mov_b32_e32 v12, 0
	v_mov_b32_e32 v13, 0
	v_mov_b32_e32 v14, 0
	v_mov_b32_e32 v15, 0
	v_mov_b32_e32 v16, 0
	v_mov_b32_e32 v17, 0
	v_mov_b32_e32 v18, 0
	v_mov_b32_e32 v19, 0
	v_mov_b32_e32 v20, 0
	v_mov_b32_e32 v21, 0
	v_mov_b32_e32 v22, 0
	v_mov_b32_e32 v23, 0
	v_mov_b32_e32 v24, 0
	v_mov_b32_e32 v25, 0
	v_mov_b32_e32 v26, 0
	v_mov_b32_e32 v27, 0
	v_mov_b32_e32 v28, 0
	v_mov_b32_e32 v29, 0
	v_mov_b32_e32 v30, 0
	v_mov_b32_e32 v31, 0
	v_mov_b32_e32 v32, 0
	v_mov_b32_e32 v33, 0
	v_mov_b32_e32 v34, 0
	v_mov_b32_e32 v35, 0
	v_mov_b32_e32 v36, 0
	v_mov_b32_e32 v37, 0
	v_mov_b32_e32 v38, 0
	v_mov_b32_e32 v39, 0
	v_mov_b32_e32 v40, 0
	v_mov_b32_e32 v41, 0
	v_mov_b32_e32 v42, 0
	v_mov_b32_e32 v43, 0
	v_mov_b32_e32 v44, 0
	v_mov_b32_e32 v45, 0
	v_mov_b32_e32 v46, 0
	v_mov_b32_e32 v47, 0
	v_mov_b32_e32 v48, 0
	v_mov_b32_e32 v49, 0
	v_mov_b32_e32 v50, 0
	v_mov_b32_e32 v51, 0
	v_mov_b32_e32 v52, 0
	v_mov_b32_e32 v53, 0
	v_mov_b32_e32 v54, 0
	v_mov_b32_e32 v55, 0
	v_mov_b32_e32 v56, 0
	v_mov_b32_e32 v57, 0
	v_mov_b32_e32 v58, 0
	v_mov_b32_e32 v59, 0
	v_mov_b32_e32 v60, 0
	v_mov_b32_e32 v61, 0
	v_mov_b32_e32 v62, 0
	v_mov_b32_e32 v63, 0
	v_mov_b32_e32 v64, 0
	v_mov_b32_e32 v65, 0
	v_mov_b32_e32 v218, 0
	v_mov_b32_e32 v146, 0
	v_mov_b32_e32 v154, 0x3f803f80
	v_mov_b32_e32 v147, 0
	v_mov_b32_e32 v155, 0x3f803f80
	v_mov_b32_e32 v148, 0
	v_mov_b32_e32 v156, 0x3f803f80
	v_mov_b32_e32 v149, 0
	v_mov_b32_e32 v157, 0x3f803f80
	v_mov_b32_e32 v208, 0xc0e00000
	v_mov_b32_e32 v209, 0xc0e00000
	v_mov_b32_e32 v210, 0xc0e00000
	v_mov_b32_e32 v211, 0xc0e00000
	v_mov_b32_e32 v219, 0
	v_mov_b32_e32 v150, 0
	v_mov_b32_e32 v154, 0x3f803f80
	v_mov_b32_e32 v151, 0
	v_mov_b32_e32 v155, 0x3f803f80
	v_mov_b32_e32 v152, 0
	v_mov_b32_e32 v156, 0x3f803f80
	v_mov_b32_e32 v153, 0
	v_mov_b32_e32 v157, 0x3f803f80
	v_mov_b32_e32 v212, 0xc0e00000
	v_mov_b32_e32 v213, 0xc0e00000
	v_mov_b32_e32 v214, 0xc0e00000
	v_mov_b32_e32 v215, 0xc0e00000
	s_mov_b32 s41, 0
	s_mov_b32 s42, 0
	s_waitcnt vmcnt(0)
	s_barrier
